# chunk_scan: + exact in-order vmcnt waits (loads 4 steps ahead) and MFMA hazard spacing restored after the address-math removal
# baseline (speedup 1.0000x reference)
.LBB0_915:
	s_or_b64 exec, exec, s[12:13]
	v_lshrrev_b32_e32 v0, 4, v53
	v_and_b32_e32 v2, 15, v53
	v_bfe_u32 v55, v53, 1, 3
	v_bfe_u32 v107, v53, 4, 2
	v_lshlrev_b32_e32 v54, 7, v2
	v_bitop3_b32 v0, v0, v55, 3 bitop3:0x6c
	v_lshl_or_b32 v204, v0, 4, v54
	v_bitop3_b32 v0, v107, v55, 4 bitop3:0x36
	v_ashrrev_i32_e32 v1, 2, v53
	v_lshl_or_b32 v205, v0, 4, v54
	v_lshlrev_b32_e32 v0, 3, v107
	v_and_b32_e32 v108, -16, v1
	v_lshl_or_b32 v206, v2, 5, v0
	v_lshlrev_b32_e32 v54, 4, v2
	v_bfi_b32 v1, -16, v1, v53
	v_ashrrev_i32_e32 v53, 31, v52
	v_lshl_or_b32 v207, v107, 10, v54
	v_lshlrev_b32_e32 v208, 4, v107
	v_lshlrev_b64 v[110:111], 23, v[52:53]
	s_waitcnt lgkmcnt(0)
	s_barrier
	ds_read_b128 v[76:79], v204
	ds_read_b128 v[92:95], v204 offset:2048
	ds_read_b128 v[72:75], v205
	ds_read_b128 v[88:91], v205 offset:2048
	v_lshl_or_b32 v209, v1, 5, v0
	ds_read_b64 v[0:1], v206 offset:4096
	ds_read_b128 v[60:63], v207 offset:4608
	ds_read_b128 v[56:59], v207 offset:4864
	ds_read_b128 v[52:55], v207 offset:5120
	ds_read_b128 v[84:87], v208 offset:10816
	ds_read_b128 v[68:71], v208 offset:10880
	ds_read_b128 v[96:99], v208 offset:10752
	ds_read_b128 v[64:67], v207 offset:5376
	ds_read_b64 v[100:101], v209 offset:8704
	ds_read_b128 v[80:83], v208 offset:10944
	v_add_u32_e32 v105, v105, v106
	s_movk_i32 s12, 0x2b00
	v_mad_i64_i32 v[182:183], s[12:13], v105, s12, v[102:103]
	v_and_b32_e32 v103, 7, v104
	v_lshlrev_b32_e32 v102, 13, v107
	v_lshlrev_b32_e32 v103, 8, v103
	v_ashrrev_i32_e32 v109, 31, v108
	v_or3_b32 v110, v110, v102, v103
	v_lshl_add_u64 v[184:185], v[108:109], 2, v[110:111]
	v_mov_b32_e32 v106, 0
	v_lshl_or_b32 v184, v2, 2, v184
	s_mov_b32 s34, 0
	v_mov_b32_e32 v107, v106
	v_mov_b32_e32 v108, v106
	v_mov_b32_e32 v109, v106
	v_mov_b32_e32 v110, v106
	v_mov_b32_e32 v111, v106
	v_mov_b32_e32 v112, v106
	v_mov_b32_e32 v113, v106
	v_mov_b32_e32 v114, v106
	v_mov_b32_e32 v115, v106
	v_mov_b32_e32 v116, v106
	v_mov_b32_e32 v117, v106
	v_mov_b32_e32 v118, v106
	v_mov_b32_e32 v119, v106
	v_mov_b32_e32 v120, v106
	v_mov_b32_e32 v121, v106
	v_mov_b32_e32 v248, v182
	v_add_u32_e32 v249, 0x1000, v182
	v_add_u32_e32 v250, 0x1bf08000, v184
	s_add_u32 s100, s24, 0x4c55700
	s_addc_u32 s101, s25, 0
	s_waitcnt vmcnt(0)
	s_branch .LBB0_917
.LBB0_916:
	v_cvt_pk_bf16_f32 v210, v142, v143
	v_cvt_pk_bf16_f32 v211, v144, v145
	v_cvt_pk_bf16_f32 v212, v146, v147
	v_cvt_pk_bf16_f32 v213, v148, v149
	v_cvt_pk_bf16_f32 v218, v154, v155
	v_cvt_pk_bf16_f32 v219, v156, v157
	s_nop 0
	v_lshlrev_b32_e32 v0, 16, v210
	v_and_b32_e32 v1, 0xffff0000, v210
	v_sub_f32_e32 v0, v142, v0
	v_sub_f32_e32 v1, v143, v1
	v_cvt_pk_bf16_f32 v214, v0, v1
	v_lshlrev_b32_e32 v0, 16, v211
	v_and_b32_e32 v1, 0xffff0000, v211
	v_sub_f32_e32 v0, v144, v0
	v_sub_f32_e32 v1, v145, v1
	v_mfma_f32_16x16x32_bf16 v[224:227], v[170:173], v[210:213], 0
	v_cvt_pk_bf16_f32 v215, v0, v1
	v_lshlrev_b32_e32 v0, 16, v212
	v_and_b32_e32 v1, 0xffff0000, v212
	v_sub_f32_e32 v0, v146, v0
	v_sub_f32_e32 v1, v147, v1
	v_cvt_pk_bf16_f32 v216, v0, v1
	v_lshlrev_b32_e32 v0, 16, v213
	v_and_b32_e32 v1, 0xffff0000, v213
	v_sub_f32_e32 v0, v148, v0
	v_sub_f32_e32 v1, v149, v1
	v_cvt_pk_bf16_f32 v217, v0, v1
	v_lshlrev_b32_e32 v0, 16, v218
	v_mfma_f32_16x16x32_bf16 v[170:173], v[170:173], v[214:217], v[224:227]
	v_and_b32_e32 v1, 0xffff0000, v218
	v_sub_f32_e32 v0, v154, v0
	v_sub_f32_e32 v1, v155, v1
	v_cvt_pk_bf16_f32 v222, v0, v1
	v_lshlrev_b32_e32 v0, 16, v219
	v_and_b32_e32 v1, 0xffff0000, v219
	v_cvt_pk_bf16_f32 v220, v158, v159
	v_cvt_pk_bf16_f32 v221, v160, v161
	v_sub_f32_e32 v0, v156, v0
	v_sub_f32_e32 v1, v157, v1
	v_mfma_f32_16x16x32_bf16 v[170:173], v[162:165], v[218:221], v[170:173]
	v_cvt_pk_bf16_f32 v223, v0, v1
	v_lshlrev_b32_e32 v0, 16, v220
	v_and_b32_e32 v1, 0xffff0000, v220
	v_sub_f32_e32 v0, v158, v0
	v_sub_f32_e32 v1, v159, v1
	v_cvt_pk_bf16_f32 v224, v0, v1
	v_lshlrev_b32_e32 v0, 16, v221
	v_and_b32_e32 v1, 0xffff0000, v221
	v_mov_b32_e32 v152, v3
	v_mov_b32_e32 v153, v3
	v_sub_f32_e32 v0, v160, v0
	v_sub_f32_e32 v1, v161, v1
	v_cvt_pk_bf16_f32 v225, v0, v1
	v_mov_b32_e32 v176, v3
	v_mfma_f32_16x16x32_bf16 v[162:165], v[162:165], v[222:225], v[170:173]
	v_mov_b32_e32 v177, v3
	v_pk_mul_f32 v[144:145], v[168:169], v[144:145]
	v_pk_mul_f32 v[142:143], v[166:167], v[142:143]
	v_mfma_f32_16x16x32_bf16 v[150:153], v[150:153], v[174:177], v[162:165]
	v_mfma_f32_16x16x32_bf16 v[162:165], v[118:121], v[210:213], 0
	s_nop 0
	v_mfma_f32_16x16x32_bf16 v[118:121], v[118:121], v[214:217], v[162:165]
	s_add_i32 s34, s34, 4
	v_mfma_f32_16x16x32_bf16 v[118:121], v[134:137], v[218:221], v[118:121]
	v_mfma_f32_16x16x32_bf16 v[118:121], v[134:137], v[222:225], v[118:121]
	v_mov_b32_e32 v136, v174
	v_mov_b32_e32 v137, v175
	s_nop 5
	v_cvt_pk_bf16_f32 v134, -v118, -v119
	v_cvt_pk_bf16_f32 v135, -v120, -v121
	v_lshlrev_b32_e32 v0, 16, v134
	v_and_b32_e32 v1, 0xffff0000, v134
	v_sub_f32_e64 v0, -v118, v0
	v_sub_f32_e64 v1, -v119, v1
	v_mfma_f32_16x16x32_bf16 v[142:145], v[114:117], v[134:137], v[142:145]
	v_cvt_pk_bf16_f32 v0, v0, v1
	v_lshlrev_b32_e32 v1, 16, v135
	v_and_b32_e32 v2, 0xffff0000, v135
	v_sub_f32_e64 v1, -v120, v1
	v_sub_f32_e64 v2, -v121, v2
	v_cvt_pk_bf16_f32 v1, v1, v2
	v_mov_b32_e32 v2, v3
	s_nop 1
	v_mfma_f32_16x16x32_bf16 v[118:121], v[114:117], v[0:3], v[142:145]
	v_mul_f32_e64 v116, v140, v148
	v_mul_f32_e64 v117, v141, v149
	v_pk_mul_f32 v[114:115], v[138:139], v[146:147]
	s_nop 1
	v_mfma_f32_16x16x32_bf16 v[114:117], v[110:113], v[134:137], v[114:117]
	v_mfma_f32_16x16x32_bf16 v[114:117], v[110:113], v[0:3], v[114:117]
	v_mul_f32_e64 v112, v132, v156
	v_mul_f32_e64 v113, v133, v157
	v_pk_mul_f32 v[110:111], v[130:131], v[154:155]
	s_nop 0
	s_nop 0
	v_mfma_f32_16x16x32_bf16 v[110:113], v[106:109], v[134:137], v[110:113]
	s_mov_b64 s[12:13], 0xac00
	v_mfma_f32_16x16x32_bf16 v[110:113], v[106:109], v[0:3], v[110:113]
	v_mul_f32_e64 v108, v128, v160
	v_mul_f32_e64 v109, v129, v161
	v_pk_mul_f32 v[106:107], v[126:127], v[158:159]
	v_lshl_add_u64 v[182:183], v[182:183], 0, s[12:13]
	s_mov_b64 s[12:13], 0x20000
	v_mfma_f32_16x16x32_bf16 v[106:109], v[122:125], v[134:137], v[106:109]
	v_lshl_add_u64 v[184:185], v[184:185], 0, s[12:13]
	s_andn2_b64 vcc, exec, s[40:41]
	global_store_dword v250, v150, s[24:25] offset:-4096
	v_mfma_f32_16x16x32_bf16 v[106:109], v[122:125], v[0:3], v[106:109]
	s_waitcnt lgkmcnt(9)
	v_mov_b64_e32 v[0:1], v[104:105]
	global_store_dword v250, v151, s[24:25] offset:-2048
	global_store_dword v250, v152, s[24:25]
	global_store_dword v250, v153, s[24:25] offset:2048
	v_add_u32_e32 v250, 0x8000, v250
	s_cbranch_vccz .LBB0_656
.LBB0_917:
	s_waitcnt vmcnt(21)
	ds_write_b128 v181, v[8:11] offset:11008
	s_waitcnt vmcnt(20)
	ds_write_b128 v188, v[12:15] offset:11008
	s_and_saveexec_b64 s[12:13], s[42:43]
	ds_write_b128 v189, v[16:19] offset:11008
	s_or_b64 exec, exec, s[12:13]
	s_cmpk_gt_u32 s34, 0xfa
	s_cbranch_scc1 .LBB0_923
	global_load_dwordx4 v[8:11], v248, s[100:101] offset:-4096
	s_nop 0
	global_load_dwordx4 v[12:15], v248, s[100:101]
	s_and_saveexec_b64 s[12:13], s[42:43]
	s_cbranch_execz .LBB0_922
	global_load_dwordx4 v[16:19], v249, s[100:101]

.LBB0_923:
	v_cvt_pk_bf16_f32 v122, v118, v119
	v_cvt_pk_bf16_f32 v123, v120, v121
	v_cvt_pk_bf16_f32 v124, v114, v115
	v_cvt_pk_bf16_f32 v125, v116, v117
	v_cvt_pk_bf16_f32 v130, v110, v111
	v_cvt_pk_bf16_f32 v131, v112, v113
	s_nop 0
	v_and_b32_e32 v102, 0xffff0000, v122
	v_lshlrev_b32_e32 v2, 16, v122
	v_sub_f32_e32 v102, v119, v102
	v_sub_f32_e32 v2, v118, v2
	v_cvt_pk_bf16_f32 v126, v2, v102
	v_and_b32_e32 v102, 0xffff0000, v123
	v_lshlrev_b32_e32 v2, 16, v123
	v_sub_f32_e32 v102, v121, v102
	v_sub_f32_e32 v2, v120, v2
	v_cvt_pk_bf16_f32 v127, v2, v102
	v_and_b32_e32 v102, 0xffff0000, v124
	v_lshlrev_b32_e32 v2, 16, v124
	v_sub_f32_e32 v102, v115, v102
	v_sub_f32_e32 v2, v114, v2
	v_cvt_pk_bf16_f32 v128, v2, v102
	v_and_b32_e32 v102, 0xffff0000, v125
	v_lshlrev_b32_e32 v2, 16, v125
	v_sub_f32_e32 v102, v117, v102
	v_sub_f32_e32 v2, v116, v2
	v_cvt_pk_bf16_f32 v129, v2, v102
	v_and_b32_e32 v102, 0xffff0000, v130
	v_lshlrev_b32_e32 v2, 16, v130
	v_sub_f32_e32 v102, v111, v102
	v_sub_f32_e32 v2, v110, v2
	v_cvt_pk_bf16_f32 v146, v2, v102
	v_and_b32_e32 v102, 0xffff0000, v131
	v_lshlrev_b32_e32 v2, 16, v131
	v_sub_f32_e32 v102, v113, v102
	v_sub_f32_e32 v2, v112, v2
	v_cvt_pk_bf16_f32 v147, v2, v102
	s_waitcnt lgkmcnt(14)
	v_mfma_f32_16x16x32_bf16 v[102:105], v[92:95], v[122:125], 0
	v_cvt_pk_bf16_f32 v132, v106, v107
	v_cvt_pk_bf16_f32 v133, v108, v109
	s_waitcnt lgkmcnt(3)
	v_mov_b32_e32 v160, v100
	v_mfma_f32_16x16x32_bf16 v[92:95], v[92:95], v[126:129], v[102:105]
	v_lshlrev_b32_e32 v2, 16, v132
	v_sub_f32_e32 v2, v106, v2
	v_and_b32_e32 v134, 0xffff0000, v132
	v_mfma_f32_16x16x32_bf16 v[92:95], v[88:91], v[130:133], v[92:95]
	v_sub_f32_e32 v134, v107, v134
	v_cvt_pk_bf16_f32 v148, v2, v134
	v_lshlrev_b32_e32 v2, 16, v133
	v_sub_f32_e32 v2, v108, v2
	v_and_b32_e32 v102, 0xffff0000, v133
	v_sub_f32_e32 v102, v109, v102
	v_cvt_pk_bf16_f32 v149, v2, v102
	v_mov_b32_e32 v2, v3
	v_mfma_f32_16x16x32_bf16 v[88:91], v[88:91], v[146:149], v[92:95]
	v_mov_b32_e32 v102, v3
	v_mov_b32_e32 v103, v3
	v_mov_b32_e32 v161, v101
	v_mfma_f32_16x16x32_bf16 v[92:95], v[76:79], v[122:125], 0
	v_mul_f32_e64 v98, v120, v98
	v_mul_f32_e64 v99, v121, v99
	v_pk_mul_f32 v[96:97], v[118:119], v[96:97]
	s_waitcnt lgkmcnt(0)
	v_mfma_f32_16x16x32_bf16 v[154:157], v[0:3], v[100:103], v[88:91]
	s_barrier
	s_nop 1
	ds_read_b128 v[88:91], v204 offset:11008
	ds_read_b128 v[150:153], v204 offset:13056
	v_mfma_f32_16x16x32_bf16 v[102:105], v[76:79], v[126:129], v[92:95]
	ds_read_b128 v[142:145], v205 offset:11008
	s_nop 1
	ds_read_b128 v[92:95], v205 offset:13056
	ds_read_b64 v[76:77], v206 offset:15104
	ds_read_b128 v[138:141], v207 offset:15616
	v_mfma_f32_16x16x32_bf16 v[102:105], v[72:75], v[130:133], v[102:105]
	ds_read_b128 v[130:133], v207 offset:15872
	ds_read_b128 v[122:125], v207 offset:16128
	ds_read_b128 v[134:137], v208 offset:21824
	ds_read_b128 v[126:129], v208 offset:21888
	v_mfma_f32_16x16x32_bf16 v[72:75], v[72:75], v[146:149], v[102:105]
	s_nop 2
	ds_read_b128 v[100:103], v208 offset:21760
	ds_read_b128 v[118:121], v207 offset:16384
	s_nop 2
	v_cvt_pk_bf16_f32 v158, -v72, -v73
	v_cvt_pk_bf16_f32 v159, -v74, -v75
	v_lshlrev_b32_e32 v0, 16, v158
	v_and_b32_e32 v1, 0xffff0000, v158
	v_sub_f32_e64 v0, -v72, v0
	v_sub_f32_e64 v1, -v73, v1
	v_mfma_f32_16x16x32_bf16 v[96:99], v[60:63], v[158:161], v[96:99]
	v_cvt_pk_bf16_f32 v0, v0, v1
	v_lshlrev_b32_e32 v1, 16, v159
	v_and_b32_e32 v2, 0xffff0000, v159
	v_sub_f32_e64 v1, -v74, v1
	v_sub_f32_e64 v2, -v75, v2
	v_cvt_pk_bf16_f32 v1, v1, v2
	v_mov_b32_e32 v2, v3
	s_nop 1
	v_mfma_f32_16x16x32_bf16 v[96:99], v[60:63], v[0:3], v[96:99]
	v_mul_f32_e64 v62, v116, v86
	v_mul_f32_e64 v63, v117, v87
	v_pk_mul_f32 v[60:61], v[114:115], v[84:85]
	ds_read_b64 v[84:85], v209 offset:19712
	ds_read_b128 v[114:117], v208 offset:21952
	v_mfma_f32_16x16x32_bf16 v[60:63], v[56:59], v[158:161], v[60:63]
	v_mfma_f32_16x16x32_bf16 v[146:149], v[56:59], v[0:3], v[60:63]
	v_mul_f32_e64 v58, v112, v70
	v_mul_f32_e64 v59, v113, v71
	v_pk_mul_f32 v[56:57], v[110:111], v[68:69]
	s_nop 3
	v_mfma_f32_16x16x32_bf16 v[56:59], v[52:55], v[158:161], v[56:59]
	s_nop 0
	v_mfma_f32_16x16x32_bf16 v[110:113], v[52:55], v[0:3], v[56:59]
	v_mul_f32_e64 v54, v108, v82
	v_mul_f32_e64 v55, v109, v83
	v_pk_mul_f32 v[52:53], v[106:107], v[80:81]
	s_nop 0
	s_nop 0
	v_mfma_f32_16x16x32_bf16 v[52:55], v[64:67], v[158:161], v[52:55]
	global_store_dword v250, v154, s[24:25] offset:-4096
	v_mfma_f32_16x16x32_bf16 v[106:109], v[64:67], v[0:3], v[52:55]
	global_store_dword v250, v155, s[24:25] offset:-2048
	global_store_dword v250, v156, s[24:25]
	global_store_dword v250, v157, s[24:25] offset:2048
	v_add_u32_e32 v250, 0x8000, v250
	s_waitcnt vmcnt(19)
	ds_write_b128 v181, v[20:23]
	s_waitcnt vmcnt(18)
	ds_write_b128 v188, v[24:27]
	s_and_saveexec_b64 s[12:13], s[42:43]
	ds_write_b128 v189, v[28:31]
	s_or_b64 exec, exec, s[12:13]
	s_cmpk_gt_u32 s34, 0xf9
	s_cbranch_scc1 .LBB0_929
	global_load_dwordx4 v[20:23], v248, s[100:101] offset:-4096
	s_nop 0
	global_load_dwordx4 v[24:27], v248, s[100:101]
	s_and_saveexec_b64 s[12:13], s[42:43]
	s_cbranch_execz .LBB0_928
	global_load_dwordx4 v[28:31], v249, s[100:101]

.LBB0_929:
	v_cvt_pk_bf16_f32 v52, v96, v97
	v_cvt_pk_bf16_f32 v53, v98, v99
	v_cvt_pk_bf16_f32 v54, v146, v147
	v_cvt_pk_bf16_f32 v55, v148, v149
	v_cvt_pk_bf16_f32 v60, v110, v111
	v_cvt_pk_bf16_f32 v61, v112, v113
	s_nop 0
	v_lshlrev_b32_e32 v0, 16, v52
	v_and_b32_e32 v1, 0xffff0000, v52
	v_sub_f32_e32 v0, v96, v0
	v_sub_f32_e32 v1, v97, v1
	v_cvt_pk_bf16_f32 v56, v0, v1
	v_lshlrev_b32_e32 v0, 16, v53
	v_and_b32_e32 v1, 0xffff0000, v53
	v_sub_f32_e32 v0, v98, v0
	v_sub_f32_e32 v1, v99, v1
	s_waitcnt lgkmcnt(14)
	v_mfma_f32_16x16x32_bf16 v[66:69], v[150:153], v[52:55], 0
	v_cvt_pk_bf16_f32 v57, v0, v1
	v_lshlrev_b32_e32 v0, 16, v54
	v_and_b32_e32 v1, 0xffff0000, v54
	v_sub_f32_e32 v0, v146, v0
	v_sub_f32_e32 v1, v147, v1
	v_cvt_pk_bf16_f32 v58, v0, v1
	v_lshlrev_b32_e32 v0, 16, v55
	v_and_b32_e32 v1, 0xffff0000, v55
	v_sub_f32_e32 v0, v148, v0
	v_sub_f32_e32 v1, v149, v1
	v_cvt_pk_bf16_f32 v59, v0, v1
	v_lshlrev_b32_e32 v0, 16, v60
	v_mfma_f32_16x16x32_bf16 v[68:71], v[150:153], v[56:59], v[66:69]
	v_and_b32_e32 v1, 0xffff0000, v60
	v_sub_f32_e32 v0, v110, v0
	v_sub_f32_e32 v1, v111, v1
	v_cvt_pk_bf16_f32 v64, v0, v1
	v_lshlrev_b32_e32 v0, 16, v61
	v_and_b32_e32 v1, 0xffff0000, v61
	v_cvt_pk_bf16_f32 v62, v106, v107
	v_cvt_pk_bf16_f32 v63, v108, v109
	v_sub_f32_e32 v0, v112, v0
	v_sub_f32_e32 v1, v113, v1
	s_waitcnt lgkmcnt(12)
	v_mfma_f32_16x16x32_bf16 v[68:71], v[92:95], v[60:63], v[68:71]
	v_cvt_pk_bf16_f32 v65, v0, v1
	v_lshlrev_b32_e32 v0, 16, v62
	v_and_b32_e32 v1, 0xffff0000, v62
	v_mfma_f32_16x16x32_bf16 v[52:55], v[88:91], v[52:55], 0
	v_sub_f32_e32 v0, v106, v0
	v_sub_f32_e32 v1, v107, v1
	v_cvt_pk_bf16_f32 v66, v0, v1
	v_lshlrev_b32_e32 v0, 16, v63
	v_and_b32_e32 v1, 0xffff0000, v63
	v_mov_b32_e32 v78, v3
	v_mov_b32_e32 v79, v3
	v_sub_f32_e32 v0, v108, v0
	v_sub_f32_e32 v1, v109, v1
	v_cvt_pk_bf16_f32 v67, v0, v1
	v_mfma_f32_16x16x32_bf16 v[52:55], v[88:91], v[56:59], v[52:55]
	v_mov_b32_e32 v86, v3
	v_mov_b32_e32 v87, v3
	v_mfma_f32_16x16x32_bf16 v[68:71], v[92:95], v[64:67], v[68:71]
	s_waitcnt lgkmcnt(6)
	v_pk_mul_f32 v[112:113], v[128:129], v[112:113]
	v_pk_mul_f32 v[110:111], v[126:127], v[110:111]
	s_waitcnt lgkmcnt(2)
	v_pk_mul_f32 v[108:109], v[116:117], v[108:109]
	v_mfma_f32_16x16x32_bf16 v[156:159], v[76:79], v[84:87], v[68:71]
	v_mul_f32_e64 v106, v114, v106
	v_mul_f32_e64 v107, v115, v107
	s_waitcnt lgkmcnt(0)
	s_barrier
	v_mfma_f32_16x16x32_bf16 v[68:71], v[142:145], v[60:63], v[52:55]
	ds_read_b128 v[76:79], v204
	ds_read_b128 v[92:95], v204 offset:2048
	ds_read_b128 v[72:75], v205
	ds_read_b128 v[88:91], v205 offset:2048
	ds_read_b64 v[104:105], v206 offset:4096
	ds_read_b128 v[60:63], v207 offset:4608
	ds_read_b128 v[56:59], v207 offset:4864
	ds_read_b128 v[52:55], v207 offset:5120
	v_mfma_f32_16x16x32_bf16 v[64:67], v[142:145], v[64:67], v[68:71]
	v_mov_b32_e32 v144, v84
	v_mov_b32_e32 v145, v85
	s_nop 0
	v_pk_mul_f32 v[70:71], v[102:103], v[98:99]
	v_pk_mul_f32 v[68:69], v[100:101], v[96:97]
	s_nop 2
	v_cvt_pk_bf16_f32 v142, -v64, -v65
	v_cvt_pk_bf16_f32 v143, -v66, -v67
	v_lshlrev_b32_e32 v0, 16, v142
	v_and_b32_e32 v1, 0xffff0000, v142
	v_sub_f32_e64 v0, -v64, v0
	v_sub_f32_e64 v1, -v65, v1
	v_mfma_f32_16x16x32_bf16 v[68:71], v[138:141], v[142:145], v[68:71]
	v_cvt_pk_bf16_f32 v0, v0, v1
	v_lshlrev_b32_e32 v1, 16, v143
	v_and_b32_e32 v2, 0xffff0000, v143
	v_sub_f32_e64 v1, -v66, v1
	v_sub_f32_e64 v2, -v67, v2
	v_pk_mul_f32 v[66:67], v[136:137], v[148:149]
	v_pk_mul_f32 v[64:65], v[134:135], v[146:147]
	v_cvt_pk_bf16_f32 v1, v1, v2
	v_mov_b32_e32 v2, v3
	v_mfma_f32_16x16x32_bf16 v[134:137], v[130:133], v[142:145], v[64:67]
	s_nop 0
	v_mfma_f32_16x16x32_bf16 v[110:113], v[122:125], v[142:145], v[110:113]
	v_mfma_f32_16x16x32_bf16 v[106:109], v[118:121], v[142:145], v[106:109]
	s_nop 0
	v_mfma_f32_16x16x32_bf16 v[138:141], v[138:141], v[0:3], v[68:71]
	ds_read_b128 v[84:87], v208 offset:10816
	s_nop 1
	ds_read_b128 v[68:71], v208 offset:10880
	ds_read_b128 v[96:99], v208 offset:10752
	ds_read_b128 v[64:67], v207 offset:5376
	ds_read_b64 v[100:101], v209 offset:8704
	ds_read_b128 v[80:83], v208 offset:10944
	global_store_dword v250, v156, s[24:25] offset:-4096
	v_mfma_f32_16x16x32_bf16 v[146:149], v[130:133], v[0:3], v[134:137]
	global_store_dword v250, v157, s[24:25] offset:-2048
	global_store_dword v250, v158, s[24:25]
	global_store_dword v250, v159, s[24:25] offset:2048
	v_add_u32_e32 v250, 0x8000, v250
	s_waitcnt vmcnt(17)
	ds_write_b128 v181, v[32:35] offset:11008
	s_waitcnt vmcnt(16)
	ds_write_b128 v188, v[36:39] offset:11008
	v_mfma_f32_16x16x32_bf16 v[152:155], v[122:125], v[0:3], v[110:113]
	v_mfma_f32_16x16x32_bf16 v[158:161], v[118:121], v[0:3], v[106:109]
	s_and_saveexec_b64 s[12:13], s[42:43]
	ds_write_b128 v189, v[40:43] offset:11008
	s_or_b64 exec, exec, s[12:13]
	s_cmpk_gt_u32 s34, 0xf8
	s_cbranch_scc1 .LBB0_935
	global_load_dwordx4 v[32:35], v248, s[100:101] offset:-4096
	s_nop 0
	global_load_dwordx4 v[36:39], v248, s[100:101]
	s_and_saveexec_b64 s[12:13], s[42:43]
	s_cbranch_execz .LBB0_934
	global_load_dwordx4 v[40:43], v249, s[100:101]

.LBB0_935:
	v_cvt_pk_bf16_f32 v108, v138, v139
	v_cvt_pk_bf16_f32 v109, v140, v141
	v_cvt_pk_bf16_f32 v110, v146, v147
	v_cvt_pk_bf16_f32 v111, v148, v149
	v_cvt_pk_bf16_f32 v122, v152, v153
	v_cvt_pk_bf16_f32 v123, v154, v155
	s_nop 0
	v_lshlrev_b32_e32 v0, 16, v108
	v_and_b32_e32 v1, 0xffff0000, v108
	v_sub_f32_e32 v0, v138, v0
	v_sub_f32_e32 v1, v139, v1
	v_cvt_pk_bf16_f32 v112, v0, v1
	v_lshlrev_b32_e32 v0, 16, v109
	v_and_b32_e32 v1, 0xffff0000, v109
	v_sub_f32_e32 v0, v140, v0
	v_sub_f32_e32 v1, v141, v1
	s_waitcnt lgkmcnt(14)
	v_mfma_f32_16x16x32_bf16 v[116:119], v[92:95], v[108:111], 0
	v_cvt_pk_bf16_f32 v113, v0, v1
	v_lshlrev_b32_e32 v0, 16, v110
	v_and_b32_e32 v1, 0xffff0000, v110
	v_sub_f32_e32 v0, v146, v0
	v_sub_f32_e32 v1, v147, v1
	v_cvt_pk_bf16_f32 v114, v0, v1
	v_lshlrev_b32_e32 v0, 16, v111
	v_and_b32_e32 v1, 0xffff0000, v111
	v_sub_f32_e32 v0, v148, v0
	v_sub_f32_e32 v1, v149, v1
	v_cvt_pk_bf16_f32 v115, v0, v1
	v_lshlrev_b32_e32 v0, 16, v122
	v_mfma_f32_16x16x32_bf16 v[116:119], v[92:95], v[112:115], v[116:119]
	v_and_b32_e32 v1, 0xffff0000, v122
	v_sub_f32_e32 v0, v152, v0
	v_sub_f32_e32 v1, v153, v1
	v_cvt_pk_bf16_f32 v126, v0, v1
	v_lshlrev_b32_e32 v0, 16, v123
	v_and_b32_e32 v1, 0xffff0000, v123
	v_cvt_pk_bf16_f32 v124, v158, v159
	v_cvt_pk_bf16_f32 v125, v160, v161
	v_sub_f32_e32 v0, v154, v0
	v_sub_f32_e32 v1, v155, v1
	s_waitcnt lgkmcnt(12)
	v_mfma_f32_16x16x32_bf16 v[116:119], v[88:91], v[122:125], v[116:119]
	v_cvt_pk_bf16_f32 v127, v0, v1
	v_lshlrev_b32_e32 v0, 16, v124
	v_and_b32_e32 v1, 0xffff0000, v124
	v_sub_f32_e32 v0, v158, v0
	v_sub_f32_e32 v1, v159, v1
	v_cvt_pk_bf16_f32 v128, v0, v1
	v_lshlrev_b32_e32 v0, 16, v125
	v_and_b32_e32 v1, 0xffff0000, v125
	v_mov_b32_e32 v106, v3
	v_mov_b32_e32 v107, v3
	v_sub_f32_e32 v0, v160, v0
	v_sub_f32_e32 v1, v161, v1
	v_cvt_pk_bf16_f32 v129, v0, v1
	v_mov_b32_e32 v102, v3
	v_mfma_f32_16x16x32_bf16 v[116:119], v[88:91], v[126:129], v[116:119]
	v_mov_b32_e32 v103, v3
	s_waitcnt lgkmcnt(3)
	v_mov_b32_e32 v216, v100
	v_mov_b32_e32 v217, v101
	v_mfma_f32_16x16x32_bf16 v[210:213], v[104:107], v[100:103], v[116:119]
	v_mul_f32_e64 v154, v70, v154
	v_mul_f32_e64 v155, v71, v155
	v_pk_mul_f32 v[152:153], v[68:69], v[152:153]
	s_waitcnt lgkmcnt(2)
	v_pk_mul_f32 v[160:161], v[82:83], v[160:161]
	v_mfma_f32_16x16x32_bf16 v[106:109], v[76:79], v[108:111], 0
	v_mul_f32_e64 v158, v80, v158
	v_mul_f32_e64 v159, v81, v159
	s_waitcnt lgkmcnt(0)
	s_barrier
	v_mfma_f32_16x16x32_bf16 v[106:109], v[76:79], v[112:115], v[106:109]
	ds_read_b128 v[118:121], v204 offset:11008
	ds_read_b128 v[170:173], v204 offset:13056
	ds_read_b128 v[134:137], v205 offset:11008
	ds_read_b128 v[162:165], v205 offset:13056
	v_mfma_f32_16x16x32_bf16 v[122:125], v[72:75], v[122:125], v[106:109]
	ds_read_b64 v[150:151], v206 offset:15104
	ds_read_b128 v[114:117], v207 offset:15616
	ds_read_b128 v[110:113], v207 offset:15872
	ds_read_b128 v[106:109], v207 offset:16128
	v_mfma_f32_16x16x32_bf16 v[122:125], v[72:75], v[126:129], v[122:125]
	v_mul_f32_e64 v128, v98, v140
	v_mul_f32_e64 v129, v99, v141
	v_pk_mul_f32 v[126:127], v[96:97], v[138:139]
	ds_read_b128 v[138:141], v208 offset:21824
	ds_read_b128 v[130:133], v208 offset:21888
	s_nop 1
	s_nop 0
	v_cvt_pk_bf16_f32 v214, -v122, -v123
	v_cvt_pk_bf16_f32 v215, -v124, -v125
	v_lshlrev_b32_e32 v0, 16, v214
	v_and_b32_e32 v1, 0xffff0000, v214
	v_sub_f32_e64 v0, -v122, v0
	v_sub_f32_e64 v1, -v123, v1
	v_mfma_f32_16x16x32_bf16 v[126:129], v[60:63], v[214:217], v[126:129]
	v_cvt_pk_bf16_f32 v0, v0, v1
	v_lshlrev_b32_e32 v1, 16, v215
	v_and_b32_e32 v2, 0xffff0000, v215
	v_sub_f32_e64 v1, -v124, v1
	v_sub_f32_e64 v2, -v125, v2
	v_pk_mul_f32 v[124:125], v[86:87], v[148:149]
	v_pk_mul_f32 v[122:123], v[84:85], v[146:147]
	v_cvt_pk_bf16_f32 v1, v1, v2
	v_mov_b32_e32 v2, v3
	v_mfma_f32_16x16x32_bf16 v[152:155], v[52:55], v[214:217], v[152:155]
	s_cmpk_lt_u32 s34, 0xfc
	v_mfma_f32_16x16x32_bf16 v[146:149], v[56:59], v[214:217], v[122:125]
	s_cselect_b64 s[12:13], -1, 0
	s_cmpk_gt_u32 s34, 0xfb
	v_mfma_f32_16x16x32_bf16 v[158:161], v[64:67], v[214:217], v[158:161]
	s_cselect_b64 s[40:41], -1, 0
	s_and_b64 vcc, exec, s[40:41]
	v_mfma_f32_16x16x32_bf16 v[142:145], v[60:63], v[0:3], v[126:129]
	ds_read_b128 v[166:169], v208 offset:21760
	ds_read_b128 v[122:125], v207 offset:16384
	ds_read_b64 v[174:175], v209 offset:19712
	ds_read_b128 v[126:129], v208 offset:21952
	global_store_dword v250, v210, s[24:25] offset:-4096
	global_store_dword v250, v211, s[24:25] offset:-2048
	global_store_dword v250, v212, s[24:25]
	global_store_dword v250, v213, s[24:25] offset:2048
	v_add_u32_e32 v250, 0x8000, v250
	v_mfma_f32_16x16x32_bf16 v[146:149], v[56:59], v[0:3], v[146:149]
	v_mfma_f32_16x16x32_bf16 v[154:157], v[52:55], v[0:3], v[152:155]
	v_mfma_f32_16x16x32_bf16 v[158:161], v[64:67], v[0:3], v[158:161]
	s_cbranch_vccnz .LBB0_939
	s_waitcnt vmcnt(23)
	ds_write_b128 v181, v[44:47]
	s_waitcnt vmcnt(22)
	ds_write_b128 v188, v[48:51]
	s_and_saveexec_b64 s[50:51], s[42:43]
	ds_write_b128 v189, v[4:7]
	s_or_b64 exec, exec, s[50:51]
.LBB0_939:
	s_cmpk_gt_u32 s34, 0xf7
	s_cbranch_scc1 .LBB0_943
	s_waitcnt vmcnt(22)
	global_load_dwordx4 v[44:47], v248, s[100:101] offset:-4096
	s_nop 0
	global_load_dwordx4 v[48:51], v248, s[100:101]
	s_and_saveexec_b64 s[50:51], s[42:43]
	s_cbranch_execz .LBB0_942
	global_load_dwordx4 v[4:7], v249, s[100:101]
